# sp5LL: with xgall the non-last XCD leaders also defer their barrier-5 wait into the P5 K-loop (poll own XGEN) instead of spinning on TOPGEN
# speedup vs baseline: 1.0175x; 1.0003x over previous
; __device__ __forceinline__ unsigned xb_add(unsigned* p, unsigned v) { return __hip_atomic_fetch_add(p, v, __ATOMIC_RELAXED, __HIP_MEMORY_SCOPE_AGENT); }
; __device__ __forceinline__ void xcd_barrier(const XcdBarrier& b) {
;     ...
;         const unsigned old = xb_add(&bar[XB_XSUB(b.x)], 1u);
;         const unsigned gen = old / nloc;
;         if (old + 1u == (gen + 1u) * nloc) {
;             __builtin_amdgcn_fence(__ATOMIC_RELEASE, "agent");
;             asm volatile("s_waitcnt vmcnt(0)" ::: "memory");
;             const unsigned og = xb_add(&bar[XB_TOP], 1u);
.LBB0_818:
	s_andn2_saveexec_b64 s[6:7], s[6:7]
	s_cbranch_execz .LBB0_842
	v_mov_b32_e32 v248, v1
	s_mov_b64 s[6:7], exec
	buffer_inv sc1
	buffer_wbl2 sc1
	s_waitcnt lgkmcnt(0)
	s_waitcnt vmcnt(0)
	v_mbcnt_lo_u32_b32 v1, s6, 0
	v_mbcnt_hi_u32_b32 v1, s7, v1
	v_cmp_eq_u32_e32 vcc, 0, v1
	s_and_saveexec_b64 s[8:9], vcc
	s_cbranch_execz .LBB0_821
	s_bcnt1_i32_b64 s3, s[6:7]
	v_mov_b32_e32 v2, 0x83000
	v_mov_b32_e32 v3, s3
	global_atomic_add v2, v2, v3, s[68:69] offset:1024 sc0

; __device__ __forceinline__ unsigned xb_ld(unsigned* p)              { return __hip_atomic_load(p, __ATOMIC_RELAXED, __HIP_MEMORY_SCOPE_AGENT); }
; __device__ __forceinline__ unsigned xb_add(unsigned* p, unsigned v) { return __hip_atomic_fetch_add(p, v, __ATOMIC_RELAXED, __HIP_MEMORY_SCOPE_AGENT); }
; #define XB_SPIN(cond, bar) do { unsigned _sp = 0; while (cond) { __builtin_amdgcn_s_sleep(1); \
;     if ((++_sp & 255u) == 0u) { if (xb_ld(&(bar)[XB_TMO])) break; if (_sp > XB_SPIN_CAP) { atomicAdd(&(bar)[XB_TMO], 1u); break; } } } } while (0)
; __device__ __forceinline__ void xcd_barrier(const XcdBarrier& b) {
;     ...
;             const unsigned tg = og / nx;
;             if (og + 1u == (tg + 1u) * nx) xb_add(&bar[XB_TOPGEN], 1u);
;             else XB_SPIN(xb_ld(&bar[XB_TOPGEN]) == tg, bar);
.Lxg_5:
	s_and_saveexec_b64 s[6:7], vcc
	s_cbranch_execz .LBB0_837
	s_cmp_lg_u32 s100, 0
	s_cbranch_scc1 .Lsp5LL_n
	s_mov_b32 s101, 0x5555
	s_mov_b64 s[10:11], 0
	s_branch .LBB0_837
.Lsp5LL_n:
	v_mov_b32_e32 v0, 0
	global_load_dword v1, v0, s[8:9] sc1
	s_mov_b64 s[14:15], 0
	s_waitcnt vmcnt(0)
	v_cmp_eq_u32_e32 vcc, v1, v2
	s_and_saveexec_b64 s[12:13], vcc
	s_cbranch_execz .LBB0_836
	s_add_u32 s10, s68, 0x80200
	s_addc_u32 s11, s69, 0
	s_mov_b32 s3, 1
	s_branch .LBB0_825
